# ROW_GN: lnx_g/lnx_b preloaded, per-row Y/bonus/g2o chunk loads hoisted to the row top with counted vmcnt; HG_H3 state staging loads batched; plus earlier row_pre/ROW_P1/MIX_O edits
# speedup vs baseline: 1.0191x; 1.0025x over previous
; __device__ __forceinline__ float sigmoidf_(float x) { return __builtin_amdgcn_rcpf(1.0f + __expf(-x)); }
; __device__ __forceinline__ void hgrn_h3(LAS unsigned char* lds8, const int e) {
;     ...
;     for (int item = bid; item < NHI; item += gsz) {
;         const int b = item >> 9, h = (item >> 6) & 7, c = item & 63, m0 = b * SEQ + c * 64;
;         const float lb = e ? sigmoidf_(IN(13)[1024 + h * 128 + k] - IN(13)[h * 128 + k]) : 0.f;
;         __syncthreads();
;         HG_GATES(true)
.LBB0_759:
	s_and_b32 s30, s28, 0xfffff000
	s_and_b32 s31, s4, 0xfc0
	s_or_b32 s35, s30, s31
	v_add_u32_e32 v6, s35, v1
	v_mov_b64_e32 v[4:5], s[54:55]
	v_mad_i64_i32 v[4:5], s[30:31], v6, s33, v[4:5]
	v_lshl_add_u64 v[4:5], s[52:53], 2, v[4:5]
	v_lshl_add_u64 v[4:5], v[4:5], 0, v[2:3]
	s_movk_i32 s30, 0x2000
	v_add_co_u32_e32 v16, vcc, s30, v4
	s_nop 1
	v_addc_co_u32_e32 v17, vcc, 0, v5, vcc
	s_barrier
	global_load_dword v27, v[16:17], off offset:-4096
	global_load_dword v82, v[4:5], off
	s_movk_i32 s30, 0x6000
	v_add_co_u32_e32 v6, vcc, s30, v4
	s_movk_i32 s30, 0x5000
	s_nop 0
	v_addc_co_u32_e32 v7, vcc, 0, v5, vcc
	global_load_dword v84, v[6:7], off offset:2048
	v_add_co_u32_e32 v6, vcc, s30, v4
	s_mov_b32 s30, 0xd000
	s_nop 0
	v_addc_co_u32_e32 v7, vcc, 0, v5, vcc
	v_add_co_u32_e32 v18, vcc, s30, v4
	s_mov_b32 s30, 0xb000
	s_nop 0
	v_addc_co_u32_e32 v19, vcc, 0, v5, vcc
	global_load_dword v116, v[6:7], off offset:2048
	v_add_co_u32_e32 v6, vcc, s30, v4
	s_mov_b32 s30, 0x11000
	s_nop 0
	v_addc_co_u32_e32 v7, vcc, 0, v5, vcc
	global_load_dword v113, v[6:7], off
	global_load_dword v85, v[18:19], off offset:-4096
	s_waitcnt vmcnt(5)
	v_mul_f32_e32 v27, 0xbfb8aa3b, v27
	global_load_dword v16, v[16:17], off
	v_add_co_u32_e32 v6, vcc, s30, v4
	s_mov_b32 s30, 0x10000
	s_nop 0
	v_addc_co_u32_e32 v7, vcc, 0, v5, vcc
	global_load_dword v87, v[6:7], off offset:2048
	v_add_co_u32_e32 v6, vcc, s30, v4
	s_mov_b32 s30, 0x18000
	s_nop 0
	v_addc_co_u32_e32 v7, vcc, 0, v5, vcc
	v_add_co_u32_e32 v20, vcc, s30, v4
	s_mov_b32 s30, 0x16000
	s_nop 0
	v_addc_co_u32_e32 v21, vcc, 0, v5, vcc
	global_load_dword v110, v[6:7], off offset:2048
	v_add_co_u32_e32 v6, vcc, s30, v4
	s_mov_b32 s30, 0x1c000
	s_nop 0
	v_addc_co_u32_e32 v7, vcc, 0, v5, vcc
	global_load_dword v107, v[6:7], off
	v_add_co_u32_e32 v6, vcc, s30, v4
	s_mov_b32 s30, 0x1b000
	s_nop 0
	v_addc_co_u32_e32 v7, vcc, 0, v5, vcc
	global_load_dword v90, v[6:7], off offset:2048
	v_add_co_u32_e32 v6, vcc, s30, v4
	s_mov_b32 s30, 0x23000
	s_nop 0
	v_addc_co_u32_e32 v7, vcc, 0, v5, vcc
	v_add_co_u32_e32 v8, vcc, s30, v4
	s_mov_b32 s30, 0x21000
	s_nop 0
	v_addc_co_u32_e32 v9, vcc, 0, v5, vcc
	global_load_dword v104, v[6:7], off offset:2048
	v_add_co_u32_e32 v6, vcc, s30, v4
	s_mov_b32 s30, 0x27000
	s_nop 0
	v_addc_co_u32_e32 v7, vcc, 0, v5, vcc
	global_load_dword v88, v[20:21], off offset:-4096
	global_load_dword v101, v[6:7], off
	v_add_co_u32_e32 v6, vcc, s30, v4
	s_mov_b32 s30, 0x26000
	s_nop 0
	v_addc_co_u32_e32 v7, vcc, 0, v5, vcc
	global_load_dword v93, v[6:7], off offset:2048
	v_add_co_u32_e32 v6, vcc, s30, v4
	s_mov_b32 s30, 0x2e000
	s_nop 0
	v_addc_co_u32_e32 v7, vcc, 0, v5, vcc
	v_add_co_u32_e32 v10, vcc, s30, v4
	s_mov_b32 s30, 0x2c000
	s_nop 0
	v_addc_co_u32_e32 v11, vcc, 0, v5, vcc
	global_load_dword v98, v[6:7], off offset:2048
	v_add_co_u32_e32 v6, vcc, s30, v4
	s_mov_b32 s30, 0x32000
	s_nop 0
	v_addc_co_u32_e32 v7, vcc, 0, v5, vcc
	global_load_dword v94, v[10:11], off offset:-4096
	global_load_dword v95, v[6:7], off
	v_add_co_u32_e32 v6, vcc, s30, v4
	s_mov_b32 s30, 0x31000
	s_nop 0
	v_addc_co_u32_e32 v7, vcc, 0, v5, vcc
	global_load_dword v96, v[6:7], off offset:2048
	v_add_co_u32_e32 v6, vcc, s30, v4
	s_mov_b32 s30, 0x39000
	s_nop 0
	v_addc_co_u32_e32 v7, vcc, 0, v5, vcc
	v_add_co_u32_e32 v12, vcc, s30, v4
	s_mov_b32 s30, 0x37000
	s_nop 0
	v_addc_co_u32_e32 v13, vcc, 0, v5, vcc
	global_load_dword v92, v[6:7], off offset:2048
	v_add_co_u32_e32 v6, vcc, s30, v4
	s_mov_b32 s30, 0x3d000
	s_nop 0
	v_addc_co_u32_e32 v7, vcc, 0, v5, vcc
	global_load_dword v125, v[12:13], off offset:-4096
	global_load_dword v89, v[6:7], off
	v_add_co_u32_e32 v6, vcc, s30, v4
	s_mov_b32 s30, 0x3c000
	s_nop 0
	v_addc_co_u32_e32 v7, vcc, 0, v5, vcc
	global_load_dword v126, v[6:7], off offset:2048
	v_add_co_u32_e32 v6, vcc, s30, v4
	s_mov_b32 s30, 0x44000
	s_nop 0
	v_addc_co_u32_e32 v7, vcc, 0, v5, vcc
	v_add_co_u32_e32 v14, vcc, s30, v4
	s_mov_b32 s30, 0x42000
	s_nop 0
	v_addc_co_u32_e32 v15, vcc, 0, v5, vcc
	global_load_dword v86, v[6:7], off offset:2048
	v_add_co_u32_e32 v6, vcc, s30, v4
	s_mov_b32 s30, 0x48000
	s_nop 0
	v_addc_co_u32_e32 v7, vcc, 0, v5, vcc
	global_load_dword v127, v[14:15], off offset:-4096
	global_load_dword v83, v[6:7], off
	v_add_co_u32_e32 v6, vcc, s30, v4
	s_mov_b32 s30, 0x47000
	s_nop 0
	v_addc_co_u32_e32 v7, vcc, 0, v5, vcc
	global_load_dword v128, v[6:7], off offset:2048
	v_add_co_u32_e32 v6, vcc, s30, v4
	s_mov_b32 s30, 0x4f000
	s_nop 0
	v_addc_co_u32_e32 v7, vcc, 0, v5, vcc
	global_load_dword v26, v[6:7], off offset:2048
	v_add_co_u32_e32 v6, vcc, s30, v4
	v_exp_f32_e32 v27, v27
	s_nop 0
	v_addc_co_u32_e32 v7, vcc, 0, v5, vcc
	s_mov_b32 s30, 0x4d000
	v_add_co_u32_e32 v22, vcc, s30, v4
	s_mov_b32 s30, 0x53000
	s_nop 0
	v_addc_co_u32_e32 v23, vcc, 0, v5, vcc
	global_load_dword v91, v[8:9], off offset:-4096
	global_load_dword v24, v[22:23], off
	global_load_dword v129, v[6:7], off offset:-4096
	v_add_co_u32_e32 v22, vcc, s30, v4
	v_add_f32_e32 v27, 1.0, v27
	s_nop 0
	v_addc_co_u32_e32 v23, vcc, 0, v5, vcc
	s_mov_b32 s30, 0x52000
	v_rcp_f32_e32 v27, v27
	global_load_dword v130, v[22:23], off offset:2048
	v_add_co_u32_e32 v22, vcc, s30, v4
	s_nop 1
	v_addc_co_u32_e32 v23, vcc, 0, v5, vcc
	global_load_dword v22, v[22:23], off offset:2048
	v_sub_f32_e32 v23, 1.0, v25
	v_fma_f32 v97, v23, v27, v25
	v_sub_f32_e32 v27, 1.0, v27
	v_mul_f32_e32 v122, v23, v27
	s_waitcnt vmcnt(31)
	v_mul_f32_e32 v27, 0xbfb8aa3b, v82
	v_exp_f32_e32 v27, v27
	v_cmp_gt_f32_e32 vcc, s29, v97
	v_add_f32_e32 v27, 1.0, v27
	v_rcp_f32_e32 v27, v27
	v_cndmask_b32_e64 v99, 0, 32, vcc
	v_ldexp_f32 v97, v97, v99
	v_log_f32_e32 v97, v97
	v_mul_f32_e32 v27, v82, v27
	v_mul_f32_e32 v124, 0x3db504f3, v27
	s_waitcnt vmcnt(30)
	v_mul_f32_e32 v27, 0xbfb8aa3b, v84
	v_exp_f32_e32 v27, v27
	v_mul_f32_e32 v99, 0x3f317217, v97
	v_fma_f32 v99, v97, s69, -v99
	v_fmac_f32_e32 v99, 0x3377d1cf, v97
	v_add_f32_e32 v27, 1.0, v27
	v_rcp_f32_e32 v121, v27
	v_fmac_f32_e32 v99, 0x3f317217, v97
	v_cmp_lt_f32_e64 s[30:31], |v97|, s60
	v_fma_f32 v27, v23, v121, v25
	s_nop 0
	v_cndmask_b32_e64 v97, v97, v99, s[30:31]
	v_cndmask_b32_e32 v99, 0, v153, vcc
	v_cmp_gt_f32_e32 vcc, s29, v27
	v_sub_f32_e32 v97, v97, v99
	v_add_f32_e32 v123, 0, v97
	v_cndmask_b32_e64 v82, 0, 32, vcc
	v_ldexp_f32 v27, v27, v82
	v_log_f32_e32 v27, v27
	s_nop 0
	v_mul_f32_e32 v82, 0x3f317217, v27
	v_fma_f32 v82, v27, s69, -v82
	v_fmac_f32_e32 v82, 0x3377d1cf, v27
	v_fmac_f32_e32 v82, 0x3f317217, v27
	v_cmp_lt_f32_e64 s[30:31], |v27|, s60
	s_nop 1
	v_cndmask_b32_e64 v27, v27, v82, s[30:31]
	v_cndmask_b32_e32 v82, 0, v153, vcc
	v_sub_f32_e32 v27, v27, v82
	v_add_f32_e32 v120, v123, v27
	s_waitcnt vmcnt(27)
	v_mul_f32_e32 v27, 0xbfb8aa3b, v85
	v_exp_f32_e32 v27, v27
	s_nop 0
	v_add_f32_e32 v27, 1.0, v27
	v_rcp_f32_e32 v119, v27
	s_nop 0
	v_fma_f32 v27, v23, v119, v25
	v_cmp_gt_f32_e32 vcc, s29, v27
	s_nop 1
	v_cndmask_b32_e64 v82, 0, 32, vcc
	v_ldexp_f32 v27, v27, v82
	v_log_f32_e32 v27, v27
	s_nop 0
	v_mul_f32_e32 v82, 0x3f317217, v27
	v_fma_f32 v82, v27, s69, -v82
	v_fmac_f32_e32 v82, 0x3377d1cf, v27
	v_fmac_f32_e32 v82, 0x3f317217, v27
	v_cmp_lt_f32_e64 s[30:31], |v27|, s60
	s_nop 1
	v_cndmask_b32_e64 v27, v27, v82, s[30:31]
	v_cndmask_b32_e32 v82, 0, v153, vcc
	v_sub_f32_e32 v27, v27, v82
	v_add_f32_e32 v118, v120, v27
	s_waitcnt vmcnt(25)
	v_mul_f32_e32 v27, 0xbfb8aa3b, v87
	v_exp_f32_e32 v27, v27
	s_nop 0
	v_add_f32_e32 v27, 1.0, v27
	v_rcp_f32_e32 v117, v27
	s_nop 0
	v_fma_f32 v27, v23, v117, v25
	v_cmp_gt_f32_e32 vcc, s29, v27
	s_nop 1
	v_cndmask_b32_e64 v82, 0, 32, vcc
	v_ldexp_f32 v27, v27, v82
	v_log_f32_e32 v27, v27
	s_nop 0
	v_mul_f32_e32 v82, 0x3f317217, v27
	v_fma_f32 v82, v27, s69, -v82
	v_fmac_f32_e32 v82, 0x3377d1cf, v27
	v_fmac_f32_e32 v82, 0x3f317217, v27
	v_cmp_lt_f32_e64 s[30:31], |v27|, s60
	s_nop 1
	v_cndmask_b32_e64 v27, v27, v82, s[30:31]
	v_cndmask_b32_e32 v82, 0, v153, vcc
	v_sub_f32_e32 v27, v27, v82
	v_add_f32_e32 v115, v118, v27
	s_waitcnt vmcnt(20)
	v_mul_f32_e32 v27, 0xbfb8aa3b, v88
	v_exp_f32_e32 v27, v27
	s_nop 0
	v_add_f32_e32 v27, 1.0, v27
	v_rcp_f32_e32 v114, v27
	s_nop 0
	v_fma_f32 v27, v23, v114, v25
	v_cmp_gt_f32_e32 vcc, s29, v27
	s_nop 1
	v_cndmask_b32_e64 v82, 0, 32, vcc
	v_ldexp_f32 v27, v27, v82
	v_log_f32_e32 v27, v27
	s_nop 0
	v_mul_f32_e32 v82, 0x3f317217, v27
	v_fma_f32 v82, v27, s69, -v82
	v_fmac_f32_e32 v82, 0x3377d1cf, v27
	v_fmac_f32_e32 v82, 0x3f317217, v27
	v_cmp_lt_f32_e64 s[30:31], |v27|, s60
	s_nop 1
	v_cndmask_b32_e64 v27, v27, v82, s[30:31]
	v_cndmask_b32_e32 v82, 0, v153, vcc
	v_sub_f32_e32 v27, v27, v82
	v_add_f32_e32 v112, v115, v27
	v_mul_f32_e32 v27, 0xbfb8aa3b, v90
	v_exp_f32_e32 v27, v27
	s_nop 0
	v_add_f32_e32 v27, 1.0, v27
	v_rcp_f32_e32 v111, v27
	s_nop 0
	v_fma_f32 v27, v23, v111, v25
	v_cmp_gt_f32_e32 vcc, s29, v27
	s_nop 1
	v_cndmask_b32_e64 v82, 0, 32, vcc
	v_ldexp_f32 v27, v27, v82
	v_log_f32_e32 v27, v27
	s_nop 0
	v_mul_f32_e32 v82, 0x3f317217, v27
	v_fma_f32 v82, v27, s69, -v82
	v_fmac_f32_e32 v82, 0x3377d1cf, v27
	v_fmac_f32_e32 v82, 0x3f317217, v27
	v_cmp_lt_f32_e64 s[30:31], |v27|, s60
	s_nop 1
	v_cndmask_b32_e64 v27, v27, v82, s[30:31]
	v_cndmask_b32_e32 v82, 0, v153, vcc
	v_sub_f32_e32 v27, v27, v82
	v_add_f32_e32 v109, v112, v27
	s_waitcnt vmcnt(4)
	v_mul_f32_e32 v27, 0xbfb8aa3b, v91
	v_exp_f32_e32 v27, v27
	s_nop 0
	v_add_f32_e32 v27, 1.0, v27
	v_rcp_f32_e32 v108, v27
	s_nop 0
	v_fma_f32 v27, v23, v108, v25
	v_cmp_gt_f32_e32 vcc, s29, v27
	s_nop 1
	v_cndmask_b32_e64 v82, 0, 32, vcc
	v_ldexp_f32 v27, v27, v82
	v_log_f32_e32 v27, v27
	s_nop 0
	v_mul_f32_e32 v82, 0x3f317217, v27
	v_fma_f32 v82, v27, s69, -v82
	v_fmac_f32_e32 v82, 0x3377d1cf, v27
	v_fmac_f32_e32 v82, 0x3f317217, v27
	v_cmp_lt_f32_e64 s[30:31], |v27|, s60
	s_nop 1
	v_cndmask_b32_e64 v27, v27, v82, s[30:31]
	v_cndmask_b32_e32 v82, 0, v153, vcc
	v_sub_f32_e32 v27, v27, v82
	v_add_f32_e32 v106, v109, v27
	v_mul_f32_e32 v27, 0xbfb8aa3b, v93
	v_exp_f32_e32 v27, v27
	s_nop 0
	v_add_f32_e32 v27, 1.0, v27
	v_rcp_f32_e32 v105, v27
	s_nop 0
	v_fma_f32 v27, v23, v105, v25
	v_cmp_gt_f32_e32 vcc, s29, v27
	s_nop 1
	v_cndmask_b32_e64 v82, 0, 32, vcc
	v_ldexp_f32 v27, v27, v82
	v_log_f32_e32 v27, v27
	s_nop 0
	v_mul_f32_e32 v82, 0x3f317217, v27
	v_fma_f32 v82, v27, s69, -v82
	v_fmac_f32_e32 v82, 0x3377d1cf, v27
	v_fmac_f32_e32 v82, 0x3f317217, v27
	v_cmp_lt_f32_e64 s[30:31], |v27|, s60
	s_nop 1
	v_cndmask_b32_e64 v27, v27, v82, s[30:31]
	v_cndmask_b32_e32 v82, 0, v153, vcc
	v_sub_f32_e32 v27, v27, v82
	v_add_f32_e32 v103, v106, v27
	v_mul_f32_e32 v27, 0xbfb8aa3b, v94
	v_exp_f32_e32 v27, v27
	s_nop 0
	v_add_f32_e32 v27, 1.0, v27
	v_rcp_f32_e32 v102, v27
	s_nop 0
	v_fma_f32 v27, v23, v102, v25
	v_cmp_gt_f32_e32 vcc, s29, v27
	s_nop 1
	v_cndmask_b32_e64 v82, 0, 32, vcc
	v_ldexp_f32 v27, v27, v82
	v_log_f32_e32 v27, v27
	s_nop 0
	v_mul_f32_e32 v82, 0x3f317217, v27
	v_fma_f32 v82, v27, s69, -v82
	v_fmac_f32_e32 v82, 0x3377d1cf, v27
	v_fmac_f32_e32 v82, 0x3f317217, v27
	v_cmp_lt_f32_e64 s[30:31], |v27|, s60
	s_nop 1
	v_cndmask_b32_e64 v27, v27, v82, s[30:31]
	v_cndmask_b32_e32 v82, 0, v153, vcc
	v_sub_f32_e32 v27, v27, v82
	v_add_f32_e32 v100, v103, v27
	v_mul_f32_e32 v27, 0xbfb8aa3b, v96
	v_exp_f32_e32 v27, v27
	s_nop 0
	v_add_f32_e32 v27, 1.0, v27
	v_rcp_f32_e32 v99, v27
	s_nop 0
	v_fma_f32 v27, v23, v99, v25
	v_cmp_gt_f32_e32 vcc, s29, v27
	s_nop 1
	v_cndmask_b32_e64 v82, 0, 32, vcc
; __device__ __forceinline__ unsigned short bf1(float f) { return (unsigned short)(pk2(f, 0.f) & 0xffffu); }
; __device__ __forceinline__ void hgrn_h3(LAS unsigned char* lds8, const int e) {
;     ...
;         { const float* vs = PROJ + (size_t)(m0 + 16 * J) * IN_EVEN + 2048 + h * 128 + k;
; #pragma unroll
;           for (int jj = 0; jj < 16; ++jj) VT[k * RS64 + 16 * J + jj] = bf1(vs[(size_t)jj * IN_EVEN]); }
	v_ldexp_f32 v27, v27, v82
	v_log_f32_e32 v27, v27
	s_nop 0
	v_mul_f32_e32 v82, 0x3f317217, v27
	v_fma_f32 v82, v27, s69, -v82
	v_fmac_f32_e32 v82, 0x3377d1cf, v27
	v_fmac_f32_e32 v82, 0x3f317217, v27
	v_cmp_lt_f32_e64 s[30:31], |v27|, s60
	s_nop 1
	v_cndmask_b32_e64 v27, v27, v82, s[30:31]
	v_cndmask_b32_e32 v82, 0, v153, vcc
	v_sub_f32_e32 v27, v27, v82
	v_add_f32_e32 v97, v100, v27
	v_mul_f32_e32 v27, 0xbfb8aa3b, v125
	v_exp_f32_e32 v27, v27
	s_nop 0
	v_add_f32_e32 v27, 1.0, v27
	v_rcp_f32_e32 v96, v27
	s_nop 0
	v_fma_f32 v27, v23, v96, v25
	v_cmp_gt_f32_e32 vcc, s29, v27
	s_nop 1
	v_cndmask_b32_e64 v82, 0, 32, vcc
	v_ldexp_f32 v27, v27, v82
	v_log_f32_e32 v27, v27
	s_nop 0
	v_mul_f32_e32 v82, 0x3f317217, v27
	v_fma_f32 v82, v27, s69, -v82
	v_fmac_f32_e32 v82, 0x3377d1cf, v27
	v_fmac_f32_e32 v82, 0x3f317217, v27
	v_cmp_lt_f32_e64 s[30:31], |v27|, s60
	s_nop 1
	v_cndmask_b32_e64 v27, v27, v82, s[30:31]
	v_cndmask_b32_e32 v82, 0, v153, vcc
	v_sub_f32_e32 v27, v27, v82
	v_add_f32_e32 v94, v97, v27
	v_mul_f32_e32 v27, 0xbfb8aa3b, v126
	v_exp_f32_e32 v27, v27
	s_nop 0
	v_add_f32_e32 v27, 1.0, v27
	v_rcp_f32_e32 v93, v27
	s_nop 0
	v_fma_f32 v27, v23, v93, v25
	v_cmp_gt_f32_e32 vcc, s29, v27
	s_nop 1
	v_cndmask_b32_e64 v82, 0, 32, vcc
	v_ldexp_f32 v27, v27, v82
	v_log_f32_e32 v27, v27
	s_nop 0
	v_mul_f32_e32 v82, 0x3f317217, v27
	v_fma_f32 v82, v27, s69, -v82
	v_fmac_f32_e32 v82, 0x3377d1cf, v27
	v_fmac_f32_e32 v82, 0x3f317217, v27
	v_cmp_lt_f32_e64 s[30:31], |v27|, s60
	s_nop 1
	v_cndmask_b32_e64 v27, v27, v82, s[30:31]
	v_cndmask_b32_e32 v82, 0, v153, vcc
	v_sub_f32_e32 v27, v27, v82
	v_add_f32_e32 v91, v94, v27
	v_mul_f32_e32 v27, 0xbfb8aa3b, v127
	v_exp_f32_e32 v27, v27
	s_nop 0
	v_add_f32_e32 v27, 1.0, v27
	v_rcp_f32_e32 v90, v27
	s_nop 0
	v_fma_f32 v27, v23, v90, v25
	v_cmp_gt_f32_e32 vcc, s29, v27
	s_nop 1
	v_cndmask_b32_e64 v82, 0, 32, vcc
	v_ldexp_f32 v27, v27, v82
	v_log_f32_e32 v27, v27
	s_nop 0
	v_mul_f32_e32 v82, 0x3f317217, v27
	v_fma_f32 v82, v27, s69, -v82
	v_fmac_f32_e32 v82, 0x3377d1cf, v27
	v_fmac_f32_e32 v82, 0x3f317217, v27
	v_cmp_lt_f32_e64 s[30:31], |v27|, s60
	s_nop 1
	v_cndmask_b32_e64 v27, v27, v82, s[30:31]
	v_cndmask_b32_e32 v82, 0, v153, vcc
	v_sub_f32_e32 v27, v27, v82
	v_add_f32_e32 v88, v91, v27
	v_mul_f32_e32 v27, 0xbfb8aa3b, v128
	v_exp_f32_e32 v27, v27
	s_nop 0
	v_add_f32_e32 v27, 1.0, v27
	v_rcp_f32_e32 v87, v27
	s_nop 0
	v_fma_f32 v27, v23, v87, v25
	v_cmp_gt_f32_e32 vcc, s29, v27
	s_nop 1
	v_cndmask_b32_e64 v82, 0, 32, vcc
	v_ldexp_f32 v27, v27, v82
	v_log_f32_e32 v27, v27
	s_nop 0
	v_mul_f32_e32 v82, 0x3f317217, v27
	v_fma_f32 v82, v27, s69, -v82
	v_fmac_f32_e32 v82, 0x3377d1cf, v27
	v_fmac_f32_e32 v82, 0x3f317217, v27
	v_cmp_lt_f32_e64 s[30:31], |v27|, s60
	s_nop 1
	v_cndmask_b32_e64 v27, v27, v82, s[30:31]
	v_cndmask_b32_e32 v82, 0, v153, vcc
	v_sub_f32_e32 v27, v27, v82
	v_add_f32_e32 v85, v88, v27
	s_waitcnt vmcnt(2)
	v_mul_f32_e32 v27, 0xbfb8aa3b, v129
	v_exp_f32_e32 v27, v27
	s_nop 0
	v_add_f32_e32 v27, 1.0, v27
	v_rcp_f32_e32 v84, v27
	s_nop 0
	v_fma_f32 v27, v23, v84, v25
	v_cmp_gt_f32_e32 vcc, s29, v27
	s_nop 1
	v_cndmask_b32_e64 v82, 0, 32, vcc
	v_ldexp_f32 v27, v27, v82
	v_log_f32_e32 v27, v27
	s_nop 0
	v_mul_f32_e32 v82, 0x3f317217, v27
	v_fma_f32 v82, v27, s69, -v82
	v_fmac_f32_e32 v82, 0x3377d1cf, v27
	v_fmac_f32_e32 v82, 0x3f317217, v27
	v_cmp_lt_f32_e64 s[30:31], |v27|, s60
	s_nop 1
	v_cndmask_b32_e64 v27, v27, v82, s[30:31]
	v_cndmask_b32_e32 v82, 0, v153, vcc
	v_sub_f32_e32 v27, v27, v82
	v_add_f32_e32 v82, v85, v27
	s_waitcnt vmcnt(1)
	v_mul_f32_e32 v27, 0xbfb8aa3b, v130
	v_exp_f32_e32 v27, v27
	s_nop 0
	v_add_f32_e32 v27, 1.0, v27
	v_rcp_f32_e32 v27, v27
	s_nop 0
	v_fmac_f32_e32 v25, v23, v27
	v_cmp_gt_f32_e32 vcc, s29, v25
	s_nop 1
	v_cndmask_b32_e64 v125, 0, 32, vcc
	v_ldexp_f32 v25, v25, v125
	v_log_f32_e32 v25, v25
	s_nop 0
	v_mul_f32_e32 v125, 0x3f317217, v25
	v_fma_f32 v125, v25, s69, -v125
	v_fmac_f32_e32 v125, 0x3377d1cf, v25
	v_fmac_f32_e32 v125, 0x3f317217, v25
	v_cmp_lt_f32_e64 s[30:31], |v25|, s60
	s_nop 1
	v_cndmask_b32_e64 v25, v25, v125, s[30:31]
	v_cndmask_b32_e32 v125, 0, v153, vcc
	v_sub_f32_e32 v25, v25, v125
	s_movk_i32 s30, 0x7000
	v_add_f32_e32 v25, v82, v25
	v_add_co_u32_e32 v126, vcc, s30, v4
	ds_write_b32 v48, v25
	s_nop 0
	v_addc_co_u32_e32 v127, vcc, 0, v5, vcc
	s_mov_b32 s30, 0x12000
	global_load_dword v17, v[126:127], off offset:2048
	s_nop 0
	global_load_dword v18, v[18:19], off
	v_add_co_u32_e32 v126, vcc, s30, v4
	s_mov_b32 s30, 0x1d000
	s_nop 0
	v_addc_co_u32_e32 v127, vcc, 0, v5, vcc
	global_load_dword v19, v[126:127], off offset:2048
	s_nop 0
	global_load_dword v20, v[20:21], off
	v_add_co_u32_e32 v126, vcc, s30, v4
	s_mov_b32 s30, 0x28000
	s_nop 0
	v_addc_co_u32_e32 v127, vcc, 0, v5, vcc
	global_load_dword v21, v[126:127], off offset:2048
	global_load_dword v125, v[8:9], off
	v_add_co_u32_e32 v8, vcc, s30, v4
	s_mov_b32 s30, 0x33000
	s_nop 0
	v_addc_co_u32_e32 v9, vcc, 0, v5, vcc
	global_load_dword v8, v[8:9], off offset:2048
	s_waitcnt vmcnt(6)
; __device__ __forceinline__ unsigned short bf1(float f) { return (unsigned short)(pk2(f, 0.f) & 0xffffu); }
; __device__ __forceinline__ void hgrn_h3(LAS unsigned char* lds8, const int e) {
;     ...
;         { const float* vs = PROJ + (size_t)(m0 + 16 * J) * IN_EVEN + 2048 + h * 128 + k;
; #pragma unroll
;           for (int jj = 0; jj < 16; ++jj) VT[k * RS64 + 16 * J + jj] = bf1(vs[(size_t)jj * IN_EVEN]); }
;         { const float* Sp = LBUF + (size_t)item * 16384;
; #pragma unroll
;           for (int i = 0; i < 8; ++i) { const int idx = tid + 512 * i, kk_ = idx >> 5, v4 = (idx & 31) * 4; const f32x4 sv = *(const f32x4*)(Sp + kk_ * 128 + v4);
;               ST[(v4 + 0) * RS128 + kk_] = bf1(sv[0]); ST[(v4 + 1) * RS128 + kk_] = bf1(sv[1]); ST[(v4 + 2) * RS128 + kk_] = bf1(sv[2]); ST[(v4 + 3) * RS128 + kk_] = bf1(sv[3]); } }
;     ...
; #pragma unroll
;           for (int jj = 0; jj < 16; ++jj) { const int i = 16 * J + jj;
;               Qt[i * RS128 + k] = bf1(qg[jj] * __expf(gl[jj])); Qb[i * RS128 + k] = bf1(qg[jj] * __expf(gs + gl[jj]));
	v_cvt_pk_bf16_f32 v126, v16, v17
	s_waitcnt vmcnt(4)
	v_cvt_pk_bf16_f32 v127, v18, v19
	s_waitcnt vmcnt(2)
	v_cvt_pk_bf16_f32 v128, v20, v21
	s_waitcnt vmcnt(0)
	v_cvt_pk_bf16_f32 v129, v125, v8
	global_load_dword v8, v[10:11], off
	v_add_co_u32_e32 v10, vcc, s30, v4
	ds_write_b128 v49, v[126:129]
	s_nop 0
	v_addc_co_u32_e32 v11, vcc, 0, v5, vcc
	s_mov_b32 s30, 0x3e000
	global_load_dword v9, v[10:11], off offset:2048
	s_nop 0
	global_load_dword v10, v[12:13], off
	v_add_co_u32_e32 v12, vcc, s30, v4
	s_mov_b32 s30, 0x49000
	s_nop 0
	v_addc_co_u32_e32 v13, vcc, 0, v5, vcc
	global_load_dword v11, v[12:13], off offset:2048
	s_nop 0
	global_load_dword v12, v[14:15], off
	v_add_co_u32_e32 v14, vcc, s30, v4
	s_mov_b32 s30, 0x54000
	s_nop 0
	v_addc_co_u32_e32 v15, vcc, 0, v5, vcc
	v_add_co_u32_e32 v4, vcc, s30, v4
	global_load_dword v13, v[14:15], off offset:2048
	s_nop 0
	global_load_dword v6, v[6:7], off
	v_addc_co_u32_e32 v5, vcc, 0, v5, vcc
	global_load_dword v4, v[4:5], off offset:2048
	s_waitcnt vmcnt(4)
	v_cvt_pk_bf16_f32 v5, v10, v11
	s_waitcnt vmcnt(0)
	v_cvt_pk_bf16_f32 v7, v6, v4
	v_cvt_pk_bf16_f32 v6, v12, v13
	v_cvt_pk_bf16_f32 v4, v8, v9
	ds_write_b128 v49, v[4:7] offset:16
	v_lshl_add_u64 v[4:5], v[32:33], 0, v[46:47]
	global_load_dwordx4 v[160:163], v[4:5], off
	v_lshl_add_u64 v[4:5], v[32:33], 0, v[44:45]
	global_load_dwordx4 v[164:167], v[4:5], off
	v_lshl_add_u64 v[4:5], v[32:33], 0, v[42:43]
	global_load_dwordx4 v[168:171], v[4:5], off
	v_lshl_add_u64 v[4:5], v[32:33], 0, v[40:41]
	global_load_dwordx4 v[172:175], v[4:5], off
	v_lshl_add_u64 v[4:5], v[32:33], 0, v[38:39]
	global_load_dwordx4 v[176:179], v[4:5], off
	v_lshl_add_u64 v[4:5], v[32:33], 0, v[36:37]
	global_load_dwordx4 v[180:183], v[4:5], off
	v_lshl_add_u64 v[4:5], v[32:33], 0, v[34:35]
	global_load_dwordx4 v[184:187], v[4:5], off
	v_lshl_add_u64 v[4:5], v[32:33], 0, v[30:31]
	global_load_dwordx4 v[188:191], v[4:5], off
	v_mul_f32_e32 v8, 0x3fb8aa3b, v123
	v_exp_f32_e32 v8, v8
	s_waitcnt vmcnt(7)
	v_cvt_pk_bf16_f32 v4, v160, s0
	ds_write_b16 v54, v4
	v_cvt_pk_bf16_f32 v4, v161, s0
	ds_write_b16 v54, v4 offset:272
	v_cvt_pk_bf16_f32 v4, v162, s0
	ds_write_b16 v54, v4 offset:544
	v_cvt_pk_bf16_f32 v4, v163, s0
	ds_write_b16 v54, v4 offset:816
	v_mul_f32_e32 v8, v124, v8
	v_cvt_pk_bf16_f32 v8, v8, s0
	s_waitcnt vmcnt(6)
	v_cvt_pk_bf16_f32 v4, v164, s0
	ds_write_b16 v55, v4
	v_cvt_pk_bf16_f32 v4, v165, s0
	ds_write_b16 v55, v4 offset:272
	v_cvt_pk_bf16_f32 v4, v166, s0
	ds_write_b16 v55, v4 offset:544
	v_cvt_pk_bf16_f32 v4, v167, s0
	ds_write_b16 v55, v4 offset:816
	s_waitcnt vmcnt(5)
	v_cvt_pk_bf16_f32 v4, v168, s0
	ds_write_b16 v56, v4
	v_cvt_pk_bf16_f32 v4, v169, s0
	ds_write_b16 v56, v4 offset:272
	v_cvt_pk_bf16_f32 v4, v170, s0
	ds_write_b16 v56, v4 offset:544
	v_cvt_pk_bf16_f32 v4, v171, s0
	ds_write_b16 v56, v4 offset:816
	s_waitcnt vmcnt(4)
	v_cvt_pk_bf16_f32 v4, v172, s0
	ds_write_b16 v57, v4
	v_cvt_pk_bf16_f32 v4, v173, s0
	ds_write_b16 v57, v4 offset:272
	v_cvt_pk_bf16_f32 v4, v174, s0
	ds_write_b16 v57, v4 offset:544
	v_cvt_pk_bf16_f32 v4, v175, s0
	ds_write_b16 v57, v4 offset:816
	s_waitcnt vmcnt(3)
	v_cvt_pk_bf16_f32 v4, v176, s0
	ds_write_b16 v58, v4
	v_cvt_pk_bf16_f32 v4, v177, s0
	ds_write_b16 v58, v4 offset:272
	v_cvt_pk_bf16_f32 v4, v178, s0
	ds_write_b16 v58, v4 offset:544
	v_cvt_pk_bf16_f32 v4, v179, s0
	ds_write_b16 v58, v4 offset:816
	s_waitcnt vmcnt(2)
	v_cvt_pk_bf16_f32 v4, v180, s0
	ds_write_b16 v59, v4
	v_cvt_pk_bf16_f32 v4, v181, s0
	ds_write_b16 v59, v4 offset:272
	v_cvt_pk_bf16_f32 v4, v182, s0
	ds_write_b16 v59, v4 offset:544
	v_cvt_pk_bf16_f32 v4, v183, s0
	ds_write_b16 v59, v4 offset:816
	s_waitcnt vmcnt(1)
	v_cvt_pk_bf16_f32 v4, v184, s0
	ds_write_b16 v60, v4
	v_cvt_pk_bf16_f32 v4, v185, s0
	ds_write_b16 v60, v4 offset:272
	v_cvt_pk_bf16_f32 v4, v186, s0
	ds_write_b16 v60, v4 offset:544
	v_cvt_pk_bf16_f32 v4, v187, s0
	ds_write_b16 v60, v4 offset:816
	s_waitcnt vmcnt(0)
	v_cvt_pk_bf16_f32 v4, v188, s0
	ds_write_b16 v61, v4
	v_cvt_pk_bf16_f32 v4, v189, s0
	ds_write_b16 v61, v4 offset:272
	v_cvt_pk_bf16_f32 v4, v190, s0
	ds_write_b16 v61, v4 offset:544
	v_cvt_pk_bf16_f32 v4, v191, s0
	ds_write_b16 v61, v4 offset:816
	s_waitcnt lgkmcnt(0)
	s_barrier
	ds_read2st64_b32 v[4:5], v50 offset1:2
	ds_read_b32 v6, v50 offset:1024
	ds_write_b16 v62, v8
	s_waitcnt lgkmcnt(2)
	v_add_f32_e32 v7, v4, v5
	s_waitcnt lgkmcnt(1)
	v_add_f32_e32 v5, v7, v6
	v_cndmask_b32_e64 v6, v5, v7, s[10:11]
	v_cndmask_b32_e64 v6, v6, v4, s[8:9]
	v_cndmask_b32_e64 v6, v6, 0, s[6:7]
	v_add_f32_e32 v8, v123, v6
	v_mul_f32_e32 v8, 0x3fb8aa3b, v8
	v_exp_f32_e32 v8, v8
	s_nop 0
	v_mul_f32_e32 v8, v124, v8
	v_cvt_pk_bf16_f32 v8, v8, s0
	ds_write_b16 v62, v8 offset:17408
	s_and_saveexec_b64 s[30:31], s[12:13]
	s_cbranch_execnz .LBB0_838
	s_or_b64 exec, exec, s[30:31]
	s_and_saveexec_b64 s[30:31], s[14:15]
	s_cbranch_execnz .LBB0_839

; __device__ __forceinline__ unsigned char* WSP() { return (unsigned char*)IN(41); }
; __device__ __forceinline__ int TID() { int t = threadIdx.x; asm volatile("" : "+v"(t)); return t; }
; __device__ __forceinline__ int BID() { int b = blockIdx.x; asm volatile("" : "+s"(b)); return b; }
; __device__ __forceinline__ int GSZ() { int g = gridDim.x; asm volatile("" : "+s"(g)); return g; }
; __device__ __forceinline__ int rfl(int v) { return __builtin_amdgcn_readfirstlane(v); }
; __device__ __forceinline__ void row_gn(const Params& p, int layer) {
;     const int tid_ = TID(), lane = tid_ & 63, gw = BID() * 8 + rfl(tid_ >> 6), ngw = GSZ() * 8;
;     unsigned char* ws = WSP(); const int o = layer >> 1;
;     const float* Y = (const float*)(ws + WS_MIX);
;     const float* BONUS = (const float*)(ws + WS_XA);
;     const bf16_t* G2O = (const bf16_t*)(ws + WS_HB);
;     const float* lg = IN(36) + (size_t)o * D; const float* lb = IN(37) + (size_t)o * D;
;     bf16_t* MA = (bf16_t*)(ws + WS_MA);
;     for (int m = gw; m < M; m += ngw) {
; #pragma unroll
;         for (int j = 0; j < 8; ++j) {
;             const int c = 256 * j + 4 * lane;
;             const f32x4 y = *(const f32x4*)(Y + (size_t)m * D + c);
;             const float mean = red16((y[0] + y[1]) + (y[2] + y[3])) * (1.f / 64.f);
;             const f32x4 d = y - mean;
;             const float var = red16((d[0] * d[0] + d[1] * d[1]) + (d[2] * d[2] + d[3] * d[3])) * (1.f / 64.f);
;             const float rs = rsqrtf(var + 64e-5f);
;             const f32x4 bo = *(const f32x4*)(BONUS + (size_t)m * D + c);
;             const u32x2 gr = *(const u32x2*)(G2O + (size_t)m * D + c);
;             const f32x4 gg = *(const f32x4*)(lg + c), bb = *(const f32x4*)(lb + c);
.LBB0_898:
	s_waitcnt vmcnt(0)
	v_mov_b32_e32 v4, v146
	s_mov_b32 s2, s67
	s_load_dwordx2 s[4:5], s[0:1], 0x150
	v_readfirstlane_b32 s3, v4
	s_lshl_b32 s2, s2, 3
	s_ashr_i32 s3, s3, 6
	s_add_i32 s2, s3, s2
	s_waitcnt lgkmcnt(0)
	s_mov_b32 s5, s4
	s_movk_i32 s7, 0x148
	s_movk_i32 s4, 0x120
	s_movk_i32 s3, 0x128
	s_cmpk_gt_i32 s2, 0x20ff
	s_cbranch_scc1 .LBB0_901
	s_lshl_b32 s6, s5, 3
	s_ashr_i32 s5, s7, 31
	s_add_u32 s8, s0, s7
	s_addc_u32 s9, s1, s5
	s_ashr_i32 s5, s4, 31
	s_add_u32 s4, s0, s4
	s_addc_u32 s5, s1, s5
	s_ashr_i32 s7, s3, 31
	s_add_u32 s10, s0, s3
	s_addc_u32 s11, s1, s7
	s_load_dwordx2 s[10:11], s[10:11], 0x0
	s_nop 0
	s_load_dwordx2 s[4:5], s[4:5], 0x0
	s_nop 0
	s_load_dwordx2 s[8:9], s[8:9], 0x0
	v_readlane_b32 s3, v234, 49
	v_lshlrev_b32_e32 v0, 4, v4
	s_waitcnt lgkmcnt(0)
	s_add_u32 s10, s10, s3
	s_addc_u32 s11, s11, 0
	s_add_u32 s4, s4, s3
	v_and_b32_e32 v2, 0x3f0, v0
	s_addc_u32 s5, s5, 0
	v_or_b32_e32 v6, 0x1000, v2
	v_mov_b32_e32 v7, v3
	v_lshl_add_u64 v[14:15], s[4:5], 0, v[6:7]
	v_lshl_add_u64 v[16:17], s[10:11], 0, v[6:7]
	v_or_b32_e32 v6, 0x1400, v2
	v_lshl_add_u64 v[0:1], s[4:5], 0, v[2:3]
	v_lshl_add_u64 v[12:13], s[10:11], 0, v[2:3]
	v_lshl_add_u64 v[18:19], s[4:5], 0, v[6:7]
	v_lshl_add_u64 v[20:21], s[10:11], 0, v[6:7]
	v_or_b32_e32 v6, 0x1800, v2
	v_or_b32_e32 v2, 0x1c00, v2
	s_ashr_i32 s3, s2, 31
	v_lshl_add_u64 v[22:23], s[4:5], 0, v[6:7]
	v_lshl_add_u64 v[26:27], s[4:5], 0, v[2:3]
	v_lshl_add_u64 v[28:29], s[10:11], 0, v[2:3]
	s_lshl_b64 s[4:5], s[2:3], 12
	v_and_b32_e32 v2, 63, v4
	v_lshl_or_b32 v30, v2, 3, s4
	v_mov_b32_e32 v31, s5
	s_ashr_i32 s7, s6, 31
	s_lshl_b64 s[4:5], s[2:3], 13
	v_lshl_add_u64 v[24:25], s[10:11], 0, v[6:7]
	s_lshl_b64 s[10:11], s[6:7], 12
	v_lshl_or_b32 v32, v2, 4, s4
	v_mov_b32_e32 v33, s5
	s_lshl_b64 s[12:13], s[6:7], 13
	global_load_dwordx4 v[60:63], v[0:1], off
	global_load_dwordx4 v[64:67], v[0:1], off offset:1024
	global_load_dwordx4 v[68:71], v[0:1], off offset:2048
	global_load_dwordx4 v[72:75], v[0:1], off offset:3072
	global_load_dwordx4 v[76:79], v[14:15], off
	global_load_dwordx4 v[80:83], v[18:19], off
	global_load_dwordx4 v[84:87], v[22:23], off
	global_load_dwordx4 v[88:91], v[26:27], off
	global_load_dwordx4 v[92:95], v[12:13], off
	global_load_dwordx4 v[96:99], v[12:13], off offset:1024
	global_load_dwordx4 v[100:103], v[12:13], off offset:2048
	global_load_dwordx4 v[104:107], v[12:13], off offset:3072
	global_load_dwordx4 v[108:111], v[16:17], off
	global_load_dwordx4 v[112:115], v[20:21], off
	global_load_dwordx4 v[116:119], v[24:25], off
	global_load_dwordx4 v[120:123], v[28:29], off
.LBB0_900:
	v_lshl_add_u64 v[4:5], s[8:9], 0, v[32:33]
	v_add_co_u32_e32 v6, vcc, 0x10d00000, v4
	s_mov_b32 s3, 0x6800000
	s_nop 0
	v_addc_co_u32_e32 v7, vcc, 0, v5, vcc
	v_lshl_add_u64 v[144:145], v[6:7], 0, s[56:57]
	v_add_co_u32_e32 v158, vcc, 0x6800000, v4
	s_nop 1
	v_addc_co_u32_e32 v159, vcc, 0, v5, vcc
	v_lshl_add_u64 v[226:227], s[8:9], 0, v[30:31]
	v_lshl_add_u64 v[224:225], v[158:159], 0, s[56:57]
	v_add_co_u32_e32 v226, vcc, 0xec00000, v226
	s_nop 1
	v_addc_co_u32_e32 v227, vcc, 0, v227, vcc
	global_load_dwordx4 v[160:163], v[6:7], off
	global_load_dwordx4 v[164:167], v[6:7], off offset:1024
	global_load_dwordx4 v[168:171], v[6:7], off offset:2048
	global_load_dwordx4 v[172:175], v[6:7], off offset:3072
	global_load_dwordx4 v[176:179], v[144:145], off
	global_load_dwordx4 v[180:183], v[144:145], off offset:1024
	global_load_dwordx4 v[184:187], v[144:145], off offset:2048
	global_load_dwordx4 v[188:191], v[144:145], off offset:3072
	global_load_dwordx4 v[192:195], v[158:159], off
	global_load_dwordx2 v[124:125], v[226:227], off
	global_load_dwordx4 v[196:199], v[158:159], off offset:1024
	global_load_dwordx2 v[126:127], v[226:227], off offset:512
	global_load_dwordx4 v[200:203], v[158:159], off offset:2048
	global_load_dwordx2 v[128:129], v[226:227], off offset:1024
	global_load_dwordx4 v[204:207], v[158:159], off offset:3072
	global_load_dwordx2 v[130:131], v[226:227], off offset:1536
	global_load_dwordx4 v[208:211], v[224:225], off
	global_load_dwordx2 v[136:137], v[226:227], off offset:2048
	global_load_dwordx4 v[212:215], v[224:225], off offset:1024
	global_load_dwordx2 v[138:139], v[226:227], off offset:2560
	global_load_dwordx4 v[216:219], v[224:225], off offset:2048
	global_load_dwordx2 v[140:141], v[226:227], off offset:3072
	global_load_dwordx4 v[220:223], v[224:225], off offset:3072
	global_load_dwordx2 v[142:143], v[226:227], off offset:3584
	v_lshl_add_u64 v[52:53], s[8:9], 0, v[30:31]
	s_add_i32 s2, s2, s6
	v_lshl_add_u64 v[30:31], v[30:31], 0, s[10:11]
	v_lshl_add_u64 v[32:33], v[32:33], 0, s[12:13]
	s_cmpk_gt_i32 s2, 0x20ff
	s_waitcnt vmcnt(23)
; __device__ __forceinline__ unsigned pk2(float lo, float hi) { f32x2c v = {lo, hi}; return __builtin_bit_cast(unsigned, __builtin_convertvector(v, bf16x2c)); }
; __device__ __forceinline__ void row_gn(const Params& p, int layer) {
;     ...
;         for (int j = 0; j < 8; ++j) {
;             const int c = 256 * j + 4 * lane;
;             const f32x4 y = *(const f32x4*)(Y + (size_t)m * D + c);
;             const float mean = red16((y[0] + y[1]) + (y[2] + y[3])) * (1.f / 64.f);
;             const f32x4 d = y - mean;
;             const float var = red16((d[0] * d[0] + d[1] * d[1]) + (d[2] * d[2] + d[3] * d[3])) * (1.f / 64.f);
;             const float rs = rsqrtf(var + 64e-5f);
;             const f32x4 bo = *(const f32x4*)(BONUS + (size_t)m * D + c);
;             const u32x2 gr = *(const u32x2*)(G2O + (size_t)m * D + c);
;             const f32x4 gg = *(const f32x4*)(lg + c), bb = *(const f32x4*)(lb + c);
;             f32x4 gt; gt[0] = __builtin_bit_cast(float, gr.x << 16); gt[1] = __builtin_bit_cast(float, gr.x & 0xffff0000u); gt[2] = __builtin_bit_cast(float, gr.y << 16); gt[3] = __builtin_bit_cast(float, gr.y & 0xffff0000u);
;             const f32x4 r = (d * rs * gg + bb + bo) * gt;
;             u32x2 w; w.x = pk2(r[0], r[1]); w.y = pk2(r[2], r[3]); *(u32x2*)(MA + (size_t)m * D + c) = w;
	v_mov_b32_e32 v34, v161
	v_mov_b32_e32 v35, v162
	v_mov_b32_e32 v36, v160
	v_mov_b32_e32 v37, v163
	v_pk_add_f32 v[34:35], v[34:35], v[36:37]
	s_nop 0
	v_add_f32_e32 v2, v34, v35
	s_nop 1
	v_add_f32_dpp v2, v2, v2 quad_perm:[1,0,3,2] row_mask:0xf bank_mask:0xf bound_ctrl:1
	s_nop 1
	v_add_f32_dpp v2, v2, v2 quad_perm:[2,3,0,1] row_mask:0xf bank_mask:0xf bound_ctrl:1
	s_nop 1
	v_add_f32_dpp v2, v2, v2 row_half_mirror row_mask:0xf bank_mask:0xf bound_ctrl:1
	s_nop 1
	v_add_f32_dpp v2, v2, v2 row_mirror row_mask:0xf bank_mask:0xf bound_ctrl:1
	v_fmamk_f32 v35, v2, 0xbc800000, v161
	v_fmamk_f32 v34, v2, 0xbc800000, v160
	v_fmamk_f32 v11, v2, 0xbc800000, v163
	v_fmamk_f32 v10, v2, 0xbc800000, v162
	v_pk_mul_f32 v[8:9], v[10:11], v[10:11]
	v_pk_mul_f32 v[36:37], v[34:35], v[34:35]
	s_nop 0
	v_pk_mov_b32 v[38:39], v[36:37], v[8:9] op_sel:[1,0]
	v_mov_b32_e32 v37, v9
	v_pk_add_f32 v[8:9], v[38:39], v[36:37]
	s_nop 0
	v_add_f32_e32 v2, v8, v9
	s_nop 1
	v_add_f32_dpp v2, v2, v2 quad_perm:[1,0,3,2] row_mask:0xf bank_mask:0xf bound_ctrl:1
	s_nop 1
	v_add_f32_dpp v2, v2, v2 quad_perm:[2,3,0,1] row_mask:0xf bank_mask:0xf bound_ctrl:1
	s_nop 1
	v_add_f32_dpp v2, v2, v2 row_half_mirror row_mask:0xf bank_mask:0xf bound_ctrl:1
	s_nop 1
	v_add_f32_dpp v2, v2, v2 row_mirror row_mask:0xf bank_mask:0xf bound_ctrl:1
	v_fmamk_f32 v2, v2, 0x3c800000, v151
	v_cmp_gt_f32_e32 vcc, s29, v2
	v_mul_f32_e32 v8, 0x4b800000, v2
	s_nop 0
	v_cndmask_b32_e32 v2, v2, v8, vcc
	v_rsq_f32_e32 v2, v2
	s_nop 0
	v_mul_f32_e32 v8, 0x45800000, v2
	v_cndmask_b32_e32 v2, v2, v8, vcc
	v_add_co_u32_e32 v8, vcc, s3, v4
	s_mov_b32 s3, 0x6801000
	s_nop 0
	v_addc_co_u32_e32 v9, vcc, 0, v5, vcc
	v_add_co_u32_e32 v38, vcc, s3, v4
	s_mov_b32 s3, 0xec00000
	s_nop 0
	v_addc_co_u32_e32 v39, vcc, 0, v5, vcc
	v_add_co_u32_e32 v36, vcc, s3, v52
	s_nop 0
	v_addc_co_u32_e32 v37, vcc, 0, v53, vcc
	v_pk_mul_f32 v[34:35], v[34:35], v[2:3] op_sel_hi:[1,0]
	v_pk_mul_f32 v[10:11], v[10:11], v[2:3] op_sel_hi:[1,0]
	s_mov_b32 s3, 0x10d01000
	s_waitcnt vmcnt(14)
	v_lshlrev_b32_e32 v56, 16, v124
	v_and_b32_e32 v57, 0xffff0000, v124
	v_pk_fma_f32 v[34:35], v[60:61], v[34:35], v[92:93]
	v_pk_fma_f32 v[10:11], v[62:63], v[10:11], v[94:95]
	v_pk_add_f32 v[34:35], v[192:193], v[34:35]
	v_lshlrev_b32_e32 v54, 16, v125
	v_and_b32_e32 v55, 0xffff0000, v125
	v_pk_add_f32 v[10:11], v[194:195], v[10:11]
	v_pk_mul_f32 v[34:35], v[34:35], v[56:57]
	v_pk_mul_f32 v[10:11], v[10:11], v[54:55]
	v_cvt_pk_bf16_f32 v40, v34, v35
	v_add_co_u32_e32 v34, vcc, s61, v52
	v_cvt_pk_bf16_f32 v41, v10, v11
	s_nop 0
	v_addc_co_u32_e32 v35, vcc, 0, v53, vcc
	global_store_dwordx2 v[34:35], v[40:41], off
	s_waitcnt vmcnt(23)
	v_mov_b32_e32 v10, v165
	v_mov_b32_e32 v11, v166
	v_mov_b32_e32 v44, v164
	v_mov_b32_e32 v45, v167
	v_pk_add_f32 v[10:11], v[10:11], v[44:45]
	s_nop 0
	v_add_f32_e32 v2, v10, v11
	s_nop 1
	v_add_f32_dpp v2, v2, v2 quad_perm:[1,0,3,2] row_mask:0xf bank_mask:0xf bound_ctrl:1
	s_nop 1
	v_add_f32_dpp v2, v2, v2 quad_perm:[2,3,0,1] row_mask:0xf bank_mask:0xf bound_ctrl:1
	s_nop 1
	v_add_f32_dpp v2, v2, v2 row_half_mirror row_mask:0xf bank_mask:0xf bound_ctrl:1
	s_nop 1
	v_add_f32_dpp v2, v2, v2 row_mirror row_mask:0xf bank_mask:0xf bound_ctrl:1
	v_fmamk_f32 v11, v2, 0xbc800000, v165
	v_fmamk_f32 v10, v2, 0xbc800000, v164
	v_fmamk_f32 v43, v2, 0xbc800000, v167
	v_fmamk_f32 v42, v2, 0xbc800000, v166
	v_pk_mul_f32 v[40:41], v[42:43], v[42:43]
	v_pk_mul_f32 v[44:45], v[10:11], v[10:11]
	s_nop 0
	v_pk_mov_b32 v[46:47], v[44:45], v[40:41] op_sel:[1,0]
	v_mov_b32_e32 v45, v41
	v_pk_add_f32 v[40:41], v[46:47], v[44:45]
	s_nop 0
	v_add_f32_e32 v2, v40, v41
	s_nop 1
	v_add_f32_dpp v2, v2, v2 quad_perm:[1,0,3,2] row_mask:0xf bank_mask:0xf bound_ctrl:1
	s_nop 1
	v_add_f32_dpp v2, v2, v2 quad_perm:[2,3,0,1] row_mask:0xf bank_mask:0xf bound_ctrl:1
	s_nop 1
	v_add_f32_dpp v2, v2, v2 row_half_mirror row_mask:0xf bank_mask:0xf bound_ctrl:1
	s_nop 1
	v_add_f32_dpp v2, v2, v2 row_mirror row_mask:0xf bank_mask:0xf bound_ctrl:1
	v_fmamk_f32 v2, v2, 0x3c800000, v151
	v_cmp_gt_f32_e32 vcc, s29, v2
	v_mul_f32_e32 v40, 0x4b800000, v2
	s_nop 0
	v_cndmask_b32_e32 v2, v2, v40, vcc
	v_rsq_f32_e32 v2, v2
	s_nop 0
	v_mul_f32_e32 v40, 0x45800000, v2
	v_cndmask_b32_e32 v2, v2, v40, vcc
	v_pk_mul_f32 v[10:11], v[10:11], v[2:3] op_sel_hi:[1,0]
	v_pk_mul_f32 v[42:43], v[42:43], v[2:3] op_sel_hi:[1,0]
	s_waitcnt vmcnt(13)
	v_lshlrev_b32_e32 v56, 16, v126
	v_and_b32_e32 v57, 0xffff0000, v126
	v_pk_fma_f32 v[42:43], v[66:67], v[42:43], v[98:99]
	v_pk_fma_f32 v[10:11], v[64:65], v[10:11], v[96:97]
	v_lshlrev_b32_e32 v40, 16, v127
	v_and_b32_e32 v41, 0xffff0000, v127
	v_pk_add_f32 v[10:11], v[196:197], v[10:11]
	v_pk_add_f32 v[42:43], v[198:199], v[42:43]
	v_pk_mul_f32 v[10:11], v[10:11], v[56:57]
	v_pk_mul_f32 v[40:41], v[42:43], v[40:41]
	v_cvt_pk_bf16_f32 v10, v10, v11
	v_cvt_pk_bf16_f32 v11, v40, v41
	global_store_dwordx2 v[34:35], v[10:11], off offset:512
	s_waitcnt vmcnt(23)
; __device__ __forceinline__ unsigned pk2(float lo, float hi) { f32x2c v = {lo, hi}; return __builtin_bit_cast(unsigned, __builtin_convertvector(v, bf16x2c)); }
; __device__ __forceinline__ void row_gn(const Params& p, int layer) {
;     ...
;         for (int j = 0; j < 8; ++j) {
;             const int c = 256 * j + 4 * lane;
;             const f32x4 y = *(const f32x4*)(Y + (size_t)m * D + c);
;             const float mean = red16((y[0] + y[1]) + (y[2] + y[3])) * (1.f / 64.f);
;             const f32x4 d = y - mean;
;             const float var = red16((d[0] * d[0] + d[1] * d[1]) + (d[2] * d[2] + d[3] * d[3])) * (1.f / 64.f);
;             const float rs = rsqrtf(var + 64e-5f);
;             const f32x4 bo = *(const f32x4*)(BONUS + (size_t)m * D + c);
;             const u32x2 gr = *(const u32x2*)(G2O + (size_t)m * D + c);
;             const f32x4 gg = *(const f32x4*)(lg + c), bb = *(const f32x4*)(lb + c);
;             f32x4 gt; gt[0] = __builtin_bit_cast(float, gr.x << 16); gt[1] = __builtin_bit_cast(float, gr.x & 0xffff0000u); gt[2] = __builtin_bit_cast(float, gr.y << 16); gt[3] = __builtin_bit_cast(float, gr.y & 0xffff0000u);
;             const f32x4 r = (d * rs * gg + bb + bo) * gt;
;             u32x2 w; w.x = pk2(r[0], r[1]); w.y = pk2(r[2], r[3]); *(u32x2*)(MA + (size_t)m * D + c) = w;
	v_mov_b32_e32 v10, v169
	v_mov_b32_e32 v11, v170
	v_mov_b32_e32 v44, v168
	v_mov_b32_e32 v45, v171
	v_pk_add_f32 v[10:11], v[10:11], v[44:45]
	s_nop 0
	v_add_f32_e32 v2, v10, v11
	s_nop 1
	v_add_f32_dpp v2, v2, v2 quad_perm:[1,0,3,2] row_mask:0xf bank_mask:0xf bound_ctrl:1
	s_nop 1
	v_add_f32_dpp v2, v2, v2 quad_perm:[2,3,0,1] row_mask:0xf bank_mask:0xf bound_ctrl:1
	s_nop 1
	v_add_f32_dpp v2, v2, v2 row_half_mirror row_mask:0xf bank_mask:0xf bound_ctrl:1
	s_nop 1
	v_add_f32_dpp v2, v2, v2 row_mirror row_mask:0xf bank_mask:0xf bound_ctrl:1
	v_fmamk_f32 v11, v2, 0xbc800000, v169
	v_fmamk_f32 v10, v2, 0xbc800000, v168
	v_fmamk_f32 v43, v2, 0xbc800000, v171
	v_fmamk_f32 v42, v2, 0xbc800000, v170
	v_pk_mul_f32 v[40:41], v[42:43], v[42:43]
	v_pk_mul_f32 v[44:45], v[10:11], v[10:11]
	s_nop 0
	v_pk_mov_b32 v[46:47], v[44:45], v[40:41] op_sel:[1,0]
	v_mov_b32_e32 v45, v41
	v_pk_add_f32 v[40:41], v[46:47], v[44:45]
	s_nop 0
	v_add_f32_e32 v2, v40, v41
	s_nop 1
	v_add_f32_dpp v2, v2, v2 quad_perm:[1,0,3,2] row_mask:0xf bank_mask:0xf bound_ctrl:1
	s_nop 1
	v_add_f32_dpp v2, v2, v2 quad_perm:[2,3,0,1] row_mask:0xf bank_mask:0xf bound_ctrl:1
	s_nop 1
	v_add_f32_dpp v2, v2, v2 row_half_mirror row_mask:0xf bank_mask:0xf bound_ctrl:1
	s_nop 1
	v_add_f32_dpp v2, v2, v2 row_mirror row_mask:0xf bank_mask:0xf bound_ctrl:1
	v_fmamk_f32 v2, v2, 0x3c800000, v151
	v_cmp_gt_f32_e32 vcc, s29, v2
	v_mul_f32_e32 v40, 0x4b800000, v2
	s_nop 0
	v_cndmask_b32_e32 v2, v2, v40, vcc
	v_rsq_f32_e32 v2, v2
	s_nop 0
	v_mul_f32_e32 v40, 0x45800000, v2
	v_cndmask_b32_e32 v2, v2, v40, vcc
	v_pk_mul_f32 v[10:11], v[10:11], v[2:3] op_sel_hi:[1,0]
	v_pk_mul_f32 v[42:43], v[42:43], v[2:3] op_sel_hi:[1,0]
	s_waitcnt vmcnt(12)
	v_lshlrev_b32_e32 v56, 16, v128
	v_and_b32_e32 v57, 0xffff0000, v128
	v_pk_fma_f32 v[42:43], v[70:71], v[42:43], v[102:103]
	v_pk_fma_f32 v[10:11], v[68:69], v[10:11], v[100:101]
	v_lshlrev_b32_e32 v40, 16, v129
	v_and_b32_e32 v41, 0xffff0000, v129
	v_pk_add_f32 v[10:11], v[200:201], v[10:11]
	v_pk_add_f32 v[42:43], v[202:203], v[42:43]
	v_pk_mul_f32 v[10:11], v[10:11], v[56:57]
	v_pk_mul_f32 v[40:41], v[42:43], v[40:41]
	v_cvt_pk_bf16_f32 v10, v10, v11
	v_cvt_pk_bf16_f32 v11, v40, v41
	global_store_dwordx2 v[34:35], v[10:11], off offset:1024
	s_waitcnt vmcnt(23)
	v_mov_b32_e32 v6, v173
	v_mov_b32_e32 v7, v174
	v_mov_b32_e32 v10, v172
	v_mov_b32_e32 v11, v175
	v_pk_add_f32 v[6:7], v[6:7], v[10:11]
	s_nop 0
	v_add_f32_e32 v2, v6, v7
	s_nop 1
	v_add_f32_dpp v2, v2, v2 quad_perm:[1,0,3,2] row_mask:0xf bank_mask:0xf bound_ctrl:1
	s_nop 1
	v_add_f32_dpp v2, v2, v2 quad_perm:[2,3,0,1] row_mask:0xf bank_mask:0xf bound_ctrl:1
	s_nop 1
	v_add_f32_dpp v2, v2, v2 row_half_mirror row_mask:0xf bank_mask:0xf bound_ctrl:1
	s_nop 1
	v_add_f32_dpp v2, v2, v2 row_mirror row_mask:0xf bank_mask:0xf bound_ctrl:1
	v_fmamk_f32 v11, v2, 0xbc800000, v173
	v_fmamk_f32 v10, v2, 0xbc800000, v172
	v_fmamk_f32 v43, v2, 0xbc800000, v175
	v_fmamk_f32 v42, v2, 0xbc800000, v174
	v_pk_mul_f32 v[6:7], v[42:43], v[42:43]
	v_pk_mul_f32 v[40:41], v[10:11], v[10:11]
	s_nop 0
	v_pk_mov_b32 v[44:45], v[40:41], v[6:7] op_sel:[1,0]
	v_mov_b32_e32 v41, v7
	v_pk_add_f32 v[6:7], v[44:45], v[40:41]
	s_nop 0
	v_add_f32_e32 v2, v6, v7
	s_nop 1
	v_add_f32_dpp v2, v2, v2 quad_perm:[1,0,3,2] row_mask:0xf bank_mask:0xf bound_ctrl:1
	s_nop 1
	v_add_f32_dpp v2, v2, v2 quad_perm:[2,3,0,1] row_mask:0xf bank_mask:0xf bound_ctrl:1
	s_nop 1
	v_add_f32_dpp v2, v2, v2 row_half_mirror row_mask:0xf bank_mask:0xf bound_ctrl:1
	s_nop 1
	v_add_f32_dpp v2, v2, v2 row_mirror row_mask:0xf bank_mask:0xf bound_ctrl:1
	v_fmamk_f32 v2, v2, 0x3c800000, v151
	v_cmp_gt_f32_e32 vcc, s29, v2
	v_mul_f32_e32 v6, 0x4b800000, v2
	s_nop 0
	v_cndmask_b32_e32 v2, v2, v6, vcc
	v_rsq_f32_e32 v2, v2
	s_nop 0
	v_mul_f32_e32 v6, 0x45800000, v2
	v_cndmask_b32_e32 v2, v2, v6, vcc
	s_nop 0
	v_pk_mul_f32 v[10:11], v[10:11], v[2:3] op_sel_hi:[1,0]
	v_pk_mul_f32 v[42:43], v[42:43], v[2:3] op_sel_hi:[1,0]
	s_waitcnt vmcnt(11)
	v_lshlrev_b32_e32 v52, 16, v130
	v_and_b32_e32 v53, 0xffff0000, v130
	v_pk_fma_f32 v[42:43], v[74:75], v[42:43], v[106:107]
	v_pk_fma_f32 v[10:11], v[72:73], v[10:11], v[104:105]
	v_lshlrev_b32_e32 v40, 16, v131
	v_and_b32_e32 v41, 0xffff0000, v131
	v_pk_add_f32 v[6:7], v[204:205], v[10:11]
	v_pk_add_f32 v[8:9], v[206:207], v[42:43]
	v_pk_mul_f32 v[6:7], v[6:7], v[52:53]
	v_pk_mul_f32 v[8:9], v[8:9], v[40:41]
	v_cvt_pk_bf16_f32 v6, v6, v7
	v_cvt_pk_bf16_f32 v7, v8, v9
	v_add_co_u32_e32 v40, vcc, s3, v4
	global_store_dwordx2 v[34:35], v[6:7], off offset:1536
	s_nop 0
	v_addc_co_u32_e32 v41, vcc, 0, v5, vcc
	s_waitcnt vmcnt(23)
	v_mov_b32_e32 v8, v177
	v_mov_b32_e32 v9, v178
	v_mov_b32_e32 v10, v176
	v_mov_b32_e32 v11, v179
	v_pk_add_f32 v[8:9], v[8:9], v[10:11]
	s_nop 0
	v_add_f32_e32 v2, v8, v9
	s_nop 1
	v_add_f32_dpp v2, v2, v2 quad_perm:[1,0,3,2] row_mask:0xf bank_mask:0xf bound_ctrl:1
	s_nop 1
	v_add_f32_dpp v2, v2, v2 quad_perm:[2,3,0,1] row_mask:0xf bank_mask:0xf bound_ctrl:1
	s_nop 1
	v_add_f32_dpp v2, v2, v2 row_half_mirror row_mask:0xf bank_mask:0xf bound_ctrl:1
	s_nop 1
	v_add_f32_dpp v2, v2, v2 row_mirror row_mask:0xf bank_mask:0xf bound_ctrl:1
	v_fmamk_f32 v5, v2, 0xbc800000, v177
	v_fmamk_f32 v4, v2, 0xbc800000, v176
	v_fmamk_f32 v7, v2, 0xbc800000, v179
	v_fmamk_f32 v6, v2, 0xbc800000, v178
	v_pk_mul_f32 v[8:9], v[6:7], v[6:7]
	v_pk_mul_f32 v[10:11], v[4:5], v[4:5]
	s_nop 0
	v_pk_mov_b32 v[42:43], v[10:11], v[8:9] op_sel:[1,0]
	v_mov_b32_e32 v11, v9
	v_pk_add_f32 v[8:9], v[42:43], v[10:11]
	s_nop 0
	v_add_f32_e32 v2, v8, v9
	s_nop 1
	v_add_f32_dpp v2, v2, v2 quad_perm:[1,0,3,2] row_mask:0xf bank_mask:0xf bound_ctrl:1
	s_nop 1
	v_add_f32_dpp v2, v2, v2 quad_perm:[2,3,0,1] row_mask:0xf bank_mask:0xf bound_ctrl:1
	s_nop 1
	v_add_f32_dpp v2, v2, v2 row_half_mirror row_mask:0xf bank_mask:0xf bound_ctrl:1
	s_nop 1
	v_add_f32_dpp v2, v2, v2 row_mirror row_mask:0xf bank_mask:0xf bound_ctrl:1
	v_fmamk_f32 v2, v2, 0x3c800000, v151
	v_cmp_gt_f32_e32 vcc, s29, v2
	v_mul_f32_e32 v8, 0x4b800000, v2
	s_nop 0
	v_cndmask_b32_e32 v2, v2, v8, vcc
	v_rsq_f32_e32 v2, v2
	s_nop 0
	v_mul_f32_e32 v8, 0x45800000, v2
	v_cndmask_b32_e32 v2, v2, v8, vcc
	v_pk_mul_f32 v[4:5], v[4:5], v[2:3] op_sel_hi:[1,0]
	v_pk_mul_f32 v[6:7], v[6:7], v[2:3] op_sel_hi:[1,0]
	s_waitcnt vmcnt(10)
; __device__ __forceinline__ unsigned pk2(float lo, float hi) { f32x2c v = {lo, hi}; return __builtin_bit_cast(unsigned, __builtin_convertvector(v, bf16x2c)); }
; __device__ __forceinline__ void row_gn(const Params& p, int layer) {
;     ...
;         for (int j = 0; j < 8; ++j) {
;             const int c = 256 * j + 4 * lane;
;             const f32x4 y = *(const f32x4*)(Y + (size_t)m * D + c);
;             const float mean = red16((y[0] + y[1]) + (y[2] + y[3])) * (1.f / 64.f);
;             const f32x4 d = y - mean;
;             const float var = red16((d[0] * d[0] + d[1] * d[1]) + (d[2] * d[2] + d[3] * d[3])) * (1.f / 64.f);
;             const float rs = rsqrtf(var + 64e-5f);
;             const f32x4 bo = *(const f32x4*)(BONUS + (size_t)m * D + c);
;             const u32x2 gr = *(const u32x2*)(G2O + (size_t)m * D + c);
;             const f32x4 gg = *(const f32x4*)(lg + c), bb = *(const f32x4*)(lb + c);
;             f32x4 gt; gt[0] = __builtin_bit_cast(float, gr.x << 16); gt[1] = __builtin_bit_cast(float, gr.x & 0xffff0000u); gt[2] = __builtin_bit_cast(float, gr.y << 16); gt[3] = __builtin_bit_cast(float, gr.y & 0xffff0000u);
;             const f32x4 r = (d * rs * gg + bb + bo) * gt;
;             u32x2 w; w.x = pk2(r[0], r[1]); w.y = pk2(r[2], r[3]); *(u32x2*)(MA + (size_t)m * D + c) = w;
	v_lshlrev_b32_e32 v52, 16, v136
	v_and_b32_e32 v53, 0xffff0000, v136
	v_pk_fma_f32 v[6:7], v[78:79], v[6:7], v[110:111]
	v_pk_fma_f32 v[4:5], v[76:77], v[4:5], v[108:109]
	v_lshlrev_b32_e32 v50, 16, v137
	v_and_b32_e32 v51, 0xffff0000, v137
	v_pk_add_f32 v[4:5], v[208:209], v[4:5]
	v_pk_add_f32 v[6:7], v[210:211], v[6:7]
	v_pk_mul_f32 v[4:5], v[4:5], v[52:53]
	v_pk_mul_f32 v[6:7], v[6:7], v[50:51]
	v_cvt_pk_bf16_f32 v4, v4, v5
	v_cvt_pk_bf16_f32 v5, v6, v7
	global_store_dwordx2 v[34:35], v[4:5], off offset:2048
	s_waitcnt vmcnt(23)
	v_mov_b32_e32 v8, v181
	v_mov_b32_e32 v9, v182
	v_mov_b32_e32 v10, v180
	v_mov_b32_e32 v11, v183
	v_pk_add_f32 v[8:9], v[8:9], v[10:11]
	s_nop 0
	v_add_f32_e32 v2, v8, v9
	s_nop 1
	v_add_f32_dpp v2, v2, v2 quad_perm:[1,0,3,2] row_mask:0xf bank_mask:0xf bound_ctrl:1
	s_nop 1
	v_add_f32_dpp v2, v2, v2 quad_perm:[2,3,0,1] row_mask:0xf bank_mask:0xf bound_ctrl:1
	s_nop 1
	v_add_f32_dpp v2, v2, v2 row_half_mirror row_mask:0xf bank_mask:0xf bound_ctrl:1
	s_nop 1
	v_add_f32_dpp v2, v2, v2 row_mirror row_mask:0xf bank_mask:0xf bound_ctrl:1
	v_fmamk_f32 v5, v2, 0xbc800000, v181
	v_fmamk_f32 v4, v2, 0xbc800000, v180
	v_fmamk_f32 v7, v2, 0xbc800000, v183
	v_fmamk_f32 v6, v2, 0xbc800000, v182
	v_pk_mul_f32 v[8:9], v[6:7], v[6:7]
	v_pk_mul_f32 v[10:11], v[4:5], v[4:5]
	s_nop 0
	v_pk_mov_b32 v[42:43], v[10:11], v[8:9] op_sel:[1,0]
	v_mov_b32_e32 v11, v9
	v_pk_add_f32 v[8:9], v[42:43], v[10:11]
	s_nop 0
	v_add_f32_e32 v2, v8, v9
	s_nop 1
	v_add_f32_dpp v2, v2, v2 quad_perm:[1,0,3,2] row_mask:0xf bank_mask:0xf bound_ctrl:1
	s_nop 1
	v_add_f32_dpp v2, v2, v2 quad_perm:[2,3,0,1] row_mask:0xf bank_mask:0xf bound_ctrl:1
	s_nop 1
	v_add_f32_dpp v2, v2, v2 row_half_mirror row_mask:0xf bank_mask:0xf bound_ctrl:1
	s_nop 1
	v_add_f32_dpp v2, v2, v2 row_mirror row_mask:0xf bank_mask:0xf bound_ctrl:1
	v_fmamk_f32 v2, v2, 0x3c800000, v151
	v_cmp_gt_f32_e32 vcc, s29, v2
	v_mul_f32_e32 v8, 0x4b800000, v2
	s_nop 0
	v_cndmask_b32_e32 v2, v2, v8, vcc
	v_rsq_f32_e32 v2, v2
	s_nop 0
	v_mul_f32_e32 v8, 0x45800000, v2
	v_cndmask_b32_e32 v2, v2, v8, vcc
	v_pk_mul_f32 v[4:5], v[4:5], v[2:3] op_sel_hi:[1,0]
	v_pk_mul_f32 v[6:7], v[6:7], v[2:3] op_sel_hi:[1,0]
	s_waitcnt vmcnt(9)
	v_lshlrev_b32_e32 v52, 16, v138
	v_and_b32_e32 v53, 0xffff0000, v138
	v_pk_fma_f32 v[6:7], v[82:83], v[6:7], v[114:115]
	v_pk_fma_f32 v[4:5], v[80:81], v[4:5], v[112:113]
	v_lshlrev_b32_e32 v42, 16, v139
	v_and_b32_e32 v43, 0xffff0000, v139
	v_pk_add_f32 v[4:5], v[212:213], v[4:5]
	v_pk_add_f32 v[6:7], v[214:215], v[6:7]
	v_pk_mul_f32 v[4:5], v[4:5], v[52:53]
	v_pk_mul_f32 v[6:7], v[6:7], v[42:43]
	v_cvt_pk_bf16_f32 v4, v4, v5
	v_cvt_pk_bf16_f32 v5, v6, v7
	global_store_dwordx2 v[34:35], v[4:5], off offset:2560
	s_waitcnt vmcnt(23)
	v_mov_b32_e32 v8, v185
	v_mov_b32_e32 v9, v186
	v_mov_b32_e32 v10, v184
	v_mov_b32_e32 v11, v187
	v_pk_add_f32 v[8:9], v[8:9], v[10:11]
	s_nop 0
	v_add_f32_e32 v2, v8, v9
	s_nop 1
	v_add_f32_dpp v2, v2, v2 quad_perm:[1,0,3,2] row_mask:0xf bank_mask:0xf bound_ctrl:1
	s_nop 1
	v_add_f32_dpp v2, v2, v2 quad_perm:[2,3,0,1] row_mask:0xf bank_mask:0xf bound_ctrl:1
	s_nop 1
	v_add_f32_dpp v2, v2, v2 row_half_mirror row_mask:0xf bank_mask:0xf bound_ctrl:1
	s_nop 1
	v_add_f32_dpp v2, v2, v2 row_mirror row_mask:0xf bank_mask:0xf bound_ctrl:1
	v_fmamk_f32 v5, v2, 0xbc800000, v185
	v_fmamk_f32 v4, v2, 0xbc800000, v184
	v_fmamk_f32 v7, v2, 0xbc800000, v187
	v_fmamk_f32 v6, v2, 0xbc800000, v186
	v_pk_mul_f32 v[8:9], v[6:7], v[6:7]
	v_pk_mul_f32 v[10:11], v[4:5], v[4:5]
	s_nop 0
	v_pk_mov_b32 v[42:43], v[10:11], v[8:9] op_sel:[1,0]
	v_mov_b32_e32 v11, v9
	v_pk_add_f32 v[8:9], v[42:43], v[10:11]
	s_nop 0
	v_add_f32_e32 v2, v8, v9
	s_nop 1
	v_add_f32_dpp v2, v2, v2 quad_perm:[1,0,3,2] row_mask:0xf bank_mask:0xf bound_ctrl:1
	s_nop 1
	v_add_f32_dpp v2, v2, v2 quad_perm:[2,3,0,1] row_mask:0xf bank_mask:0xf bound_ctrl:1
	s_nop 1
	v_add_f32_dpp v2, v2, v2 row_half_mirror row_mask:0xf bank_mask:0xf bound_ctrl:1
	s_nop 1
	v_add_f32_dpp v2, v2, v2 row_mirror row_mask:0xf bank_mask:0xf bound_ctrl:1
	v_fmamk_f32 v2, v2, 0x3c800000, v151
	v_cmp_gt_f32_e32 vcc, s29, v2
	v_mul_f32_e32 v8, 0x4b800000, v2
	s_nop 0
	v_cndmask_b32_e32 v2, v2, v8, vcc
	v_rsq_f32_e32 v2, v2
	s_nop 0
	v_mul_f32_e32 v8, 0x45800000, v2
	v_cndmask_b32_e32 v2, v2, v8, vcc
	v_pk_mul_f32 v[4:5], v[4:5], v[2:3] op_sel_hi:[1,0]
	v_pk_mul_f32 v[6:7], v[6:7], v[2:3] op_sel_hi:[1,0]
	s_waitcnt vmcnt(8)
; __device__ __forceinline__ unsigned pk2(float lo, float hi) { f32x2c v = {lo, hi}; return __builtin_bit_cast(unsigned, __builtin_convertvector(v, bf16x2c)); }
; __device__ __forceinline__ void row_gn(const Params& p, int layer) {
;     ...
;         for (int j = 0; j < 8; ++j) {
;             const int c = 256 * j + 4 * lane;
;             const f32x4 y = *(const f32x4*)(Y + (size_t)m * D + c);
;             const float mean = red16((y[0] + y[1]) + (y[2] + y[3])) * (1.f / 64.f);
;             const f32x4 d = y - mean;
;             const float var = red16((d[0] * d[0] + d[1] * d[1]) + (d[2] * d[2] + d[3] * d[3])) * (1.f / 64.f);
;             const float rs = rsqrtf(var + 64e-5f);
;             const f32x4 bo = *(const f32x4*)(BONUS + (size_t)m * D + c);
;             const u32x2 gr = *(const u32x2*)(G2O + (size_t)m * D + c);
;             const f32x4 gg = *(const f32x4*)(lg + c), bb = *(const f32x4*)(lb + c);
;             f32x4 gt; gt[0] = __builtin_bit_cast(float, gr.x << 16); gt[1] = __builtin_bit_cast(float, gr.x & 0xffff0000u); gt[2] = __builtin_bit_cast(float, gr.y << 16); gt[3] = __builtin_bit_cast(float, gr.y & 0xffff0000u);
;             const f32x4 r = (d * rs * gg + bb + bo) * gt;
;             u32x2 w; w.x = pk2(r[0], r[1]); w.y = pk2(r[2], r[3]); *(u32x2*)(MA + (size_t)m * D + c) = w;
	v_lshlrev_b32_e32 v52, 16, v140
	v_and_b32_e32 v53, 0xffff0000, v140
	v_pk_fma_f32 v[6:7], v[86:87], v[6:7], v[118:119]
	v_pk_fma_f32 v[4:5], v[84:85], v[4:5], v[116:117]
	v_lshlrev_b32_e32 v50, 16, v141
	v_and_b32_e32 v51, 0xffff0000, v141
	v_pk_add_f32 v[4:5], v[216:217], v[4:5]
	v_pk_add_f32 v[6:7], v[218:219], v[6:7]
	v_pk_mul_f32 v[4:5], v[4:5], v[52:53]
	v_pk_mul_f32 v[6:7], v[6:7], v[50:51]
	v_cvt_pk_bf16_f32 v4, v4, v5
	v_cvt_pk_bf16_f32 v5, v6, v7
	global_store_dwordx2 v[34:35], v[4:5], off offset:3072
	s_waitcnt vmcnt(23)
	v_mov_b32_e32 v8, v189
	v_mov_b32_e32 v9, v190
	v_mov_b32_e32 v10, v188
	v_mov_b32_e32 v11, v191
	v_pk_add_f32 v[8:9], v[8:9], v[10:11]
	s_nop 0
	v_add_f32_e32 v2, v8, v9
	s_nop 1
	v_add_f32_dpp v2, v2, v2 quad_perm:[1,0,3,2] row_mask:0xf bank_mask:0xf bound_ctrl:1
	s_nop 1
	v_add_f32_dpp v2, v2, v2 quad_perm:[2,3,0,1] row_mask:0xf bank_mask:0xf bound_ctrl:1
	s_nop 1
	v_add_f32_dpp v2, v2, v2 row_half_mirror row_mask:0xf bank_mask:0xf bound_ctrl:1
	s_nop 1
	v_add_f32_dpp v2, v2, v2 row_mirror row_mask:0xf bank_mask:0xf bound_ctrl:1
	v_fmamk_f32 v5, v2, 0xbc800000, v189
	v_fmamk_f32 v4, v2, 0xbc800000, v188
	v_fmamk_f32 v7, v2, 0xbc800000, v191
	v_fmamk_f32 v6, v2, 0xbc800000, v190
	v_pk_mul_f32 v[8:9], v[6:7], v[6:7]
	v_pk_mul_f32 v[10:11], v[4:5], v[4:5]
	s_nop 0
	v_pk_mov_b32 v[40:41], v[10:11], v[8:9] op_sel:[1,0]
	v_mov_b32_e32 v11, v9
	v_pk_add_f32 v[8:9], v[40:41], v[10:11]
	s_nop 0
	v_add_f32_e32 v2, v8, v9
	s_nop 1
	v_add_f32_dpp v2, v2, v2 quad_perm:[1,0,3,2] row_mask:0xf bank_mask:0xf bound_ctrl:1
	s_nop 1
	v_add_f32_dpp v2, v2, v2 quad_perm:[2,3,0,1] row_mask:0xf bank_mask:0xf bound_ctrl:1
	s_nop 1
	v_add_f32_dpp v2, v2, v2 row_half_mirror row_mask:0xf bank_mask:0xf bound_ctrl:1
	s_nop 1
	v_add_f32_dpp v2, v2, v2 row_mirror row_mask:0xf bank_mask:0xf bound_ctrl:1
	v_fmamk_f32 v2, v2, 0x3c800000, v151
	v_cmp_gt_f32_e32 vcc, s29, v2
	v_mul_f32_e32 v8, 0x4b800000, v2
	s_nop 0
	v_cndmask_b32_e32 v2, v2, v8, vcc
	v_rsq_f32_e32 v2, v2
	s_nop 0
	v_mul_f32_e32 v8, 0x45800000, v2
	v_cndmask_b32_e32 v2, v2, v8, vcc
	s_nop 0
	s_nop 0
	v_pk_mul_f32 v[4:5], v[4:5], v[2:3] op_sel_hi:[1,0]
	v_pk_mul_f32 v[6:7], v[6:7], v[2:3] op_sel_hi:[1,0]
	s_waitcnt vmcnt(7)
	v_lshlrev_b32_e32 v46, 16, v142
	v_and_b32_e32 v47, 0xffff0000, v142
	v_pk_fma_f32 v[6:7], v[90:91], v[6:7], v[122:123]
	v_pk_fma_f32 v[4:5], v[88:89], v[4:5], v[120:121]
	v_lshlrev_b32_e32 v36, 16, v143
	v_and_b32_e32 v37, 0xffff0000, v143
	v_pk_add_f32 v[4:5], v[220:221], v[4:5]
	v_pk_add_f32 v[6:7], v[222:223], v[6:7]
	v_pk_mul_f32 v[4:5], v[4:5], v[46:47]
	v_pk_mul_f32 v[6:7], v[6:7], v[36:37]
	v_cvt_pk_bf16_f32 v4, v4, v5
	v_cvt_pk_bf16_f32 v5, v6, v7
	global_store_dwordx2 v[34:35], v[4:5], off offset:3584
	s_cbranch_scc0 .LBB0_900
